# scan output store widening: Y tile written as one 8-byte-per-lane image per chunk (1 dwordx2 store instead of 4 two-byte scattered stores); GroupNorm pass reads the four images and transposes with v_p
# speedup vs baseline: 1.0252x; 1.0252x over previous
; __device__ __forceinline__ bf16x8 pk8s(f32x4 a, f32x4 b) { v4u u; u.x = pk2(a.x, a.y); u.y = pk2(a.z, a.w); u.z = pk2(b.x, b.y); u.w = pk2(b.z, b.w); return __builtin_bit_cast(bf16x8, u); }
; #define SP_BAR() asm volatile("s_waitcnt lgkmcnt(0)\n\ts_barrier" ::: "memory")
; __device__ __forceinline__ void p3_rwkv_state(Frame& F, const Args& a) {
;     ...
;         bf16* YR = (bf16*)(a.ws + WS_YR) + head * 64 + 4 * (lane & 15) + ib;
;         f32x4 H[4]; bf16x8 Hb[2];
; #pragma unroll
;         for (int t = 0; t < 4; ++t) H[t] = (f32x4){0.f, 0.f, 0.f, 0.f};
;         Hb[0] = pk8s(H[0], H[1]); Hb[1] = pk8s(H[2], H[3]);
;         ChunkOps C, N;
;         SP_BAR();
;         rw_slot_read(C, F.lds, ib, lane);
;     ...
;         for (int n = 0; n < NC; n += 2) { SP_STEP(C, N, n); SP_STEP(N, C, n + 1); }
.Lscan_consumer:
	s_lshl_b32 s1, s0, 11
	s_add_u32 s8, s72, s1
	s_addc_u32 s9, s73, 0
	s_lshl_b32 s2, s4, 9
	s_add_u32 s8, s8, s2
	s_addc_u32 s9, s9, 0
	v_lshlrev_b32_e32 v77, 4, v76
	v_lshlrev_b32_e32 v78, 3, v76
	v_lshrrev_b32_e32 v79, 4, v76
	v_and_b32_e32 v83, 15, v76
	v_lshlrev_b32_e32 v79, 6, v79
	v_lshlrev_b32_e32 v83, 3, v83
	v_lshl_add_u32 v83, v79, 7, v83
	v_mov_b32_e32 v0, 0
	v_mov_b32_e32 v1, 0
	v_mov_b32_e32 v2, 0
	v_mov_b32_e32 v3, 0
	v_mov_b32_e32 v4, 0
	v_mov_b32_e32 v5, 0
	v_mov_b32_e32 v6, 0
	v_mov_b32_e32 v7, 0
	v_mov_b32_e32 v8, 0
	v_mov_b32_e32 v9, 0
	v_mov_b32_e32 v10, 0
	v_mov_b32_e32 v11, 0
	v_mov_b32_e32 v12, 0
	v_mov_b32_e32 v13, 0
	v_mov_b32_e32 v14, 0
	v_mov_b32_e32 v15, 0
	v_mov_b32_e32 v16, 0
	v_mov_b32_e32 v17, 0
	v_mov_b32_e32 v18, 0
	v_mov_b32_e32 v19, 0
	v_mov_b32_e32 v20, 0
	v_mov_b32_e32 v21, 0
	v_mov_b32_e32 v22, 0
	v_mov_b32_e32 v23, 0
	s_barrier
	ds_read_b128 v[32:35], v77
	ds_read_b128 v[36:39], v77 offset:1024
	ds_read_b128 v[40:43], v77 offset:2048
	ds_read_b128 v[44:47], v77 offset:3072
	ds_read2st64_b64 v[96:99], v78 offset0:16 offset1:17
	ds_read_b128 v[64:67], v79 offset:9728
	ds_read_b128 v[68:71], v79 offset:9744
	ds_read_b128 v[72:75], v79 offset:9760
	ds_read_b128 v[88:91], v79 offset:9776
	ds_read2st64_b64 v[48:51], v78 offset0:12 offset1:8
	ds_read2st64_b64 v[52:55], v78 offset0:13 offset1:9
	ds_read2st64_b64 v[56:59], v78 offset0:14 offset1:10
	ds_read2st64_b64 v[60:63], v78 offset0:15 offset1:11
	ds_read_b64 v[92:93], v78 offset:9216
	s_movk_i32 s10, 0x2800
	s_mov_b32 s11, 0
	s_waitcnt lgkmcnt(9)
	v_lshlrev_b32_e32 v24, 16, v96
	v_and_b32_e32 v25, 0xffff0000, v96
	v_lshlrev_b32_e32 v26, 16, v97
	v_and_b32_e32 v27, 0xffff0000, v97
	v_lshlrev_b32_e32 v28, 16, v98
	v_and_b32_e32 v29, 0xffff0000, v98
	v_lshlrev_b32_e32 v30, 16, v99
	v_and_b32_e32 v31, 0xffff0000, v99
.Lscan_loop:
	v_add_u32_e32 v80, s10, v77
	v_add_u32_e32 v81, s10, v78
	v_add_u32_e32 v82, s10, v79
	s_add_i32 s10, s10, 0x2800
	s_cmp_eq_u32 s10, 0x25800
	s_cselect_b32 s10, 0, s10
	v_mfma_f32_16x16x32_bf16 v[24:27], v[32:35], v[16:19], v[24:27]
	v_mfma_f32_16x16x32_bf16 v[28:31], v[40:43], v[16:19], v[28:31]
	v_mfma_f32_16x16x32_bf16 v[24:27], v[36:39], v[20:23], v[24:27]
	v_mfma_f32_16x16x32_bf16 v[28:31], v[44:47], v[20:23], v[28:31]
	ds_read_b128 v[32:35], v80
	ds_read_b128 v[36:39], v80 offset:1024
	ds_read_b128 v[40:43], v80 offset:2048
	ds_read_b128 v[44:47], v80 offset:3072
	ds_read2st64_b64 v[96:99], v81 offset0:16 offset1:17
	s_waitcnt lgkmcnt(10)
	v_pk_mul_f32 v[0:1], v[64:65], v[0:1]
	v_pk_mul_f32 v[2:3], v[66:67], v[2:3]
	v_pk_mul_f32 v[4:5], v[68:69], v[4:5]
	v_pk_mul_f32 v[6:7], v[70:71], v[6:7]
	v_pk_mul_f32 v[8:9], v[72:73], v[8:9]
	v_pk_mul_f32 v[10:11], v[74:75], v[10:11]
	v_pk_mul_f32 v[12:13], v[88:89], v[12:13]
	v_pk_mul_f32 v[14:15], v[90:91], v[14:15]
	ds_read_b128 v[64:67], v82 offset:9728
	ds_read_b128 v[68:71], v82 offset:9744
	ds_read_b128 v[72:75], v82 offset:9760
	ds_read_b128 v[88:91], v82 offset:9776
	v_cvt_pk_bf16_f32 v94, v24, v25
	v_cvt_pk_bf16_f32 v95, v26, v27
	s_waitcnt lgkmcnt(9)
	s_nop 1
	v_mfma_f32_16x16x32_bf16 v[0:3], v[48:51], v[92:95], v[0:3]
	v_mfma_f32_16x16x32_bf16 v[4:7], v[52:55], v[92:95], v[4:7]
	v_mfma_f32_16x16x32_bf16 v[8:11], v[56:59], v[92:95], v[8:11]
	v_mfma_f32_16x16x32_bf16 v[12:15], v[60:63], v[92:95], v[12:15]
	v_cvt_pk_bf16_f32 v84, v28, v29
	v_cvt_pk_bf16_f32 v85, v30, v31
	ds_read2st64_b64 v[48:51], v81 offset0:12 offset1:8
	ds_read2st64_b64 v[52:55], v81 offset0:13 offset1:9
	ds_read2st64_b64 v[56:59], v81 offset0:14 offset1:10
	ds_read2st64_b64 v[60:63], v81 offset0:15 offset1:11
	ds_read_b64 v[92:93], v81 offset:9216
	global_store_dwordx2 v78, v[84:85], s[8:9]
	s_add_u32 s8, s8, 0x8000
	s_addc_u32 s9, s9, 0
	s_waitcnt lgkmcnt(9)
	v_lshlrev_b32_e32 v24, 16, v96
	v_and_b32_e32 v25, 0xffff0000, v96
	v_lshlrev_b32_e32 v26, 16, v97
	v_and_b32_e32 v27, 0xffff0000, v97
	v_lshlrev_b32_e32 v28, 16, v98
	v_and_b32_e32 v29, 0xffff0000, v98
	v_lshlrev_b32_e32 v30, 16, v99
	v_and_b32_e32 v31, 0xffff0000, v99
	v_cvt_pk_bf16_f32 v16, v0, v1
	v_cvt_pk_bf16_f32 v17, v2, v3
	v_cvt_pk_bf16_f32 v18, v4, v5
	v_cvt_pk_bf16_f32 v19, v6, v7
	v_cvt_pk_bf16_f32 v20, v8, v9
	v_cvt_pk_bf16_f32 v21, v10, v11
	v_cvt_pk_bf16_f32 v22, v12, v13
	v_cvt_pk_bf16_f32 v23, v14, v15
	v_add_u32_e32 v80, s10, v77
	v_add_u32_e32 v81, s10, v78
	v_add_u32_e32 v82, s10, v79
	s_add_i32 s10, s10, 0x2800
	s_cmp_eq_u32 s10, 0x25800
	s_cselect_b32 s10, 0, s10
	v_mfma_f32_16x16x32_bf16 v[24:27], v[32:35], v[16:19], v[24:27]
	v_mfma_f32_16x16x32_bf16 v[28:31], v[40:43], v[16:19], v[28:31]
	v_mfma_f32_16x16x32_bf16 v[24:27], v[36:39], v[20:23], v[24:27]
	v_mfma_f32_16x16x32_bf16 v[28:31], v[44:47], v[20:23], v[28:31]
	ds_read_b128 v[32:35], v80
	ds_read_b128 v[36:39], v80 offset:1024
	ds_read_b128 v[40:43], v80 offset:2048
	ds_read_b128 v[44:47], v80 offset:3072
	ds_read2st64_b64 v[96:99], v81 offset0:16 offset1:17
	s_waitcnt lgkmcnt(10)
	v_pk_mul_f32 v[0:1], v[64:65], v[0:1]
	v_pk_mul_f32 v[2:3], v[66:67], v[2:3]
	v_pk_mul_f32 v[4:5], v[68:69], v[4:5]
	v_pk_mul_f32 v[6:7], v[70:71], v[6:7]
	v_pk_mul_f32 v[8:9], v[72:73], v[8:9]
	v_pk_mul_f32 v[10:11], v[74:75], v[10:11]
	v_pk_mul_f32 v[12:13], v[88:89], v[12:13]
	v_pk_mul_f32 v[14:15], v[90:91], v[14:15]
	ds_read_b128 v[64:67], v82 offset:9728
	ds_read_b128 v[68:71], v82 offset:9744
	ds_read_b128 v[72:75], v82 offset:9760
	ds_read_b128 v[88:91], v82 offset:9776
	v_cvt_pk_bf16_f32 v94, v24, v25
	v_cvt_pk_bf16_f32 v95, v26, v27
	s_waitcnt lgkmcnt(9)
	s_nop 1
	v_mfma_f32_16x16x32_bf16 v[0:3], v[48:51], v[92:95], v[0:3]
	v_mfma_f32_16x16x32_bf16 v[4:7], v[52:55], v[92:95], v[4:7]
	v_mfma_f32_16x16x32_bf16 v[8:11], v[56:59], v[92:95], v[8:11]
	v_mfma_f32_16x16x32_bf16 v[12:15], v[60:63], v[92:95], v[12:15]
	v_cvt_pk_bf16_f32 v84, v28, v29
	v_cvt_pk_bf16_f32 v85, v30, v31
	ds_read2st64_b64 v[48:51], v81 offset0:12 offset1:8
	ds_read2st64_b64 v[52:55], v81 offset0:13 offset1:9
	ds_read2st64_b64 v[56:59], v81 offset0:14 offset1:10
	ds_read2st64_b64 v[60:63], v81 offset0:15 offset1:11
	ds_read_b64 v[92:93], v81 offset:9216
	global_store_dwordx2 v78, v[84:85], s[8:9]
	s_add_u32 s8, s8, 0x8000
	s_addc_u32 s9, s9, 0
	s_waitcnt lgkmcnt(9)
	v_lshlrev_b32_e32 v24, 16, v96
	v_and_b32_e32 v25, 0xffff0000, v96
	v_lshlrev_b32_e32 v26, 16, v97
	v_and_b32_e32 v27, 0xffff0000, v97
	v_lshlrev_b32_e32 v28, 16, v98
	v_and_b32_e32 v29, 0xffff0000, v98
	v_lshlrev_b32_e32 v30, 16, v99
	v_and_b32_e32 v31, 0xffff0000, v99
	v_cvt_pk_bf16_f32 v16, v0, v1
	v_cvt_pk_bf16_f32 v17, v2, v3
	v_cvt_pk_bf16_f32 v18, v4, v5
	v_cvt_pk_bf16_f32 v19, v6, v7
	v_cvt_pk_bf16_f32 v20, v8, v9
	v_cvt_pk_bf16_f32 v21, v10, v11
	v_cvt_pk_bf16_f32 v22, v12, v13
	v_cvt_pk_bf16_f32 v23, v14, v15
	s_barrier
	s_add_i32 s11, s11, 2
	s_cmpk_lt_u32 s11, 0x400
	s_cbranch_scc1 .Lscan_loop
	s_branch .LBB0_456

; __device__ __forceinline__ f32x4 bf4(v2u u) { return (f32x4){bflo(u.x), bfhi(u.x), bflo(u.y), bfhi(u.y)}; }
; __device__ __forceinline__ void p3_gn_chunk(const Args& a, int ch, int lane) {
;     const int n = lane & 15, rg = lane >> 4, head = ch & 15, c0 = head * 64 + 4 * n; const int t0 = (ch >> 4) * 16 + 4 * rg;
;     const bf16* YR = (const bf16*)(a.ws + WS_YR); const bf16* ZB = (const bf16*)(a.ws + WS_ZB); bf16* Y = (bf16*)(a.ws + WS_XN); const float* RK = (const float*)(a.ws + WS_RK);
;     const f32x4 lw = ld4(a.in[16] + c0), lb = ld4(a.in[17] + c0);
;     f32x4 vimg[4];
; #pragma unroll
;     for (int cb = 0; cb < 4; ++cb) vimg[cb] = bf4(*(const v2u*)(a.ws + WS_VS + (size_t)ch * 2048 + cb * 512 + lane * 8));
; #pragma unroll
;     for (int e = 0; e < 4; ++e) { const int t = t0 + e;
;         f32x4 y = bf4(*(const v2u*)(YR + (size_t)t * 1024 + c0));
;         const f32x4 g = bf4(*(const v2u*)(ZB + (size_t)t * 5120 + 4096 + c0)); const float rk = RK[(size_t)t * 16 + head];
;         const float mean = row16_sum((y.x + y.y) + (y.z + y.w)) * (1.f / 64.f);
;         y = y - mean;
;         const float rstd = __builtin_amdgcn_rsqf(row16_sum((y.x * y.x + y.y * y.y) + (y.z * y.z + y.w * y.w)) * (1.f / 64.f) + GN_EPS);
.LBB0_638:
	s_or_b64 exec, exec, s[0:1]
	v_readlane_b32 s0, v254, 39
	v_readlane_b32 s1, v254, 40
	v_readlane_b32 s60, v254, 36
	v_readlane_b32 s12, v254, 6
	s_waitcnt lgkmcnt(0)
	s_barrier
	v_mbcnt_lo_u32_b32 v0, -1, 0
	v_mbcnt_hi_u32_b32 v0, -1, v0
	s_and_b64 vcc, exec, s[0:1]
	v_readlane_b32 s61, v254, 37
	v_readlane_b32 s13, v254, 7
	v_readlane_b32 s14, v254, 8
	v_readlane_b32 s15, v254, 9
	v_readlane_b32 s24, v254, 18
	v_readlane_b32 s25, v254, 19
	v_readlane_b32 s26, v254, 20
	v_readlane_b32 s27, v254, 21
	v_readlane_b32 s16, v254, 10
	v_readlane_b32 s17, v254, 11
	v_readlane_b32 s18, v254, 12
	v_readlane_b32 s19, v254, 13
	v_readlane_b32 s20, v254, 14
	v_readlane_b32 s21, v254, 15
	v_readlane_b32 s22, v254, 16
	v_readlane_b32 s23, v254, 17
	s_cbranch_vccnz .LBB0_641
	s_add_u32 s2, s90, 0x3d00000
	s_addc_u32 s3, s91, 0
	s_ashr_i32 s65, s64, 31
	v_lshlrev_b32_e32 v1, 2, v0
	s_lshl_b64 s[0:1], s[64:65], 11
	v_and_b32_e32 v30, 60, v1
	v_ashrrev_i32_e32 v1, 2, v0
	v_lshlrev_b32_e32 v0, 3, v0
	s_add_u32 s0, s90, s0
	v_and_b32_e32 v31, -4, v1
	v_ashrrev_i32_e32 v1, 31, v0
	s_addc_u32 s1, s91, s1
	v_lshl_add_u64 v[130:131], s[72:73], 0, v[0:1]
	s_mov_b32 s98, 0x05040100
	s_mov_b32 s99, 0x07060302
	s_mov_b32 s101, 0
	v_lshl_add_u64 v[0:1], s[0:1], 0, v[0:1]
	s_mov_b64 s[0:1], 0x1d000000
	s_ashr_i32 s43, s42, 31
	v_lshl_add_u64 v[8:9], v[0:1], 0, s[0:1]
	s_lshl_b64 s[0:1], s[42:43], 11
	v_mov_b32_e32 v11, 0
	s_movk_i32 s6, 0x2800
	v_mov_b64_e32 v[12:13], s[90:91]
	s_mov_b32 s7, 0xf002000
	v_mov_b32_e32 v32, 0x3a27c5ac
	s_mov_b32 s8, s64
.LBB0_640:
	s_lshl_b32 s100, s8, 11
	v_lshl_add_u64 v[128:129], s[100:101], 0, v[130:131]
	s_and_b32 s4, s8, 15
	s_and_b32 s5, s8, -16
	v_lshl_or_b32 v0, s4, 6, v30
	v_add_u32_e32 v26, s5, v31
	s_lshl_b32 s4, s4, 2
	v_lshlrev_b32_e32 v10, 1, v0
	v_ashrrev_i32_e32 v27, 31, v26
	v_mad_i64_i32 v[28:29], s[10:11], v26, s6, v[12:13]
	s_add_u32 s4, s2, s4
	v_or_b32_e32 v34, 1, v26
	v_or_b32_e32 v36, 2, v26
	v_or_b32_e32 v22, 3, v26
	v_lshl_add_u64 v[38:39], s[72:73], 0, v[10:11]
	v_lshlrev_b64 v[40:41], 11, v[26:27]
	v_lshl_add_u64 v[28:29], v[28:29], 0, v[10:11]
	v_lshlrev_b32_e32 v23, 2, v0
	s_addc_u32 s5, s3, 0
	v_lshlrev_b64 v[42:43], 6, v[26:27]
	v_mad_i64_i32 v[44:45], s[10:11], v34, s6, v[12:13]
	v_mad_i64_i32 v[46:47], s[10:11], v36, s6, v[12:13]
	v_mad_i64_i32 v[48:49], s[10:11], v22, s6, v[12:13]
	v_lshl_add_u64 v[40:41], v[38:39], 0, v[40:41]
	v_add_co_u32_e32 v28, vcc, s7, v28
	global_load_dwordx2 v[14:15], v[8:9], off
	global_load_dwordx2 v[16:17], v[8:9], off offset:512
	global_load_dwordx2 v[18:19], v[8:9], off offset:1024
	global_load_dwordx2 v[20:21], v[8:9], off offset:1536
	global_load_dwordx4 v[0:3], v23, s[12:13]
	global_load_dwordx4 v[4:7], v23, s[14:15]
	v_lshl_add_u64 v[24:25], s[60:61], 0, v[10:11]
	v_addc_co_u32_e32 v29, vcc, 0, v29, vcc
	v_lshl_add_u64 v[42:43], s[4:5], 0, v[42:43]
	v_lshl_add_u64 v[44:45], v[44:45], 0, v[10:11]
	v_lshl_add_u64 v[46:47], v[46:47], 0, v[10:11]
	v_lshl_add_u64 v[48:49], v[48:49], 0, v[10:11]
	global_load_dwordx2 v[120:121], v[128:129], off
	global_load_dwordx2 v[122:123], v[128:129], off offset:512
	global_load_dwordx2 v[124:125], v[128:129], off offset:1024
	global_load_dwordx2 v[126:127], v[128:129], off offset:1536
	s_nop 0
	global_load_dwordx2 v[60:61], v[28:29], off
	global_load_dword v10, v[42:43], off
	v_ashrrev_i32_e32 v35, 31, v34
	v_ashrrev_i32_e32 v37, 31, v36
	v_lshlrev_b64 v[50:51], 11, v[34:35]
	v_lshlrev_b64 v[52:53], 6, v[34:35]
	v_lshlrev_b64 v[54:55], 11, v[36:37]
	v_lshlrev_b64 v[56:57], 6, v[36:37]
	v_add_co_u32_e32 v42, vcc, s7, v44
	v_lshl_add_u64 v[28:29], v[38:39], 0, v[50:51]
	s_nop 0
	v_addc_co_u32_e32 v43, vcc, 0, v45, vcc
	v_lshl_add_u64 v[44:45], s[4:5], 0, v[52:53]
	v_lshl_add_u64 v[50:51], v[38:39], 0, v[54:55]
	v_lshl_add_u64 v[52:53], s[4:5], 0, v[56:57]
	v_lshlrev_b64 v[26:27], 12, v[26:27]
	v_lshl_add_u64 v[26:27], v[24:25], 0, v[26:27]
	v_lshlrev_b64 v[34:35], 12, v[34:35]
	v_lshl_add_u64 v[34:35], v[24:25], 0, v[34:35]
	v_add_co_u32_e32 v46, vcc, s7, v46
	v_ashrrev_i32_e32 v23, 31, v22
	s_nop 0
	v_addc_co_u32_e32 v47, vcc, 0, v47, vcc
	v_lshlrev_b64 v[58:59], 11, v[22:23]
	v_lshl_add_u64 v[38:39], v[38:39], 0, v[58:59]
	v_lshlrev_b64 v[36:37], 12, v[36:37]
	v_lshl_add_u64 v[36:37], v[24:25], 0, v[36:37]
	v_add_co_u32_e32 v48, vcc, s7, v48
	s_add_i32 s8, s8, s42
	s_nop 0
	v_addc_co_u32_e32 v49, vcc, 0, v49, vcc
	v_lshl_add_u64 v[8:9], v[8:9], 0, s[0:1]
	s_cmpk_gt_i32 s8, 0x3fff
	v_lshlrev_b64 v[118:119], 6, v[22:23]
	s_nop 0
	global_load_dwordx2 v[102:103], v[42:43], off
	global_load_dword v104, v[44:45], off
	v_lshl_add_u64 v[118:119], s[4:5], 0, v[118:119]
	s_nop 0
	global_load_dwordx2 v[108:109], v[46:47], off
	global_load_dword v110, v[52:53], off
	s_nop 0
	global_load_dwordx2 v[114:115], v[48:49], off
	global_load_dword v116, v[118:119], off
	s_waitcnt vmcnt(17)
	v_lshlrev_b32_e32 v54, 16, v14
	v_and_b32_e32 v56, 0xffff0000, v14
	s_waitcnt vmcnt(16)
	v_lshlrev_b32_e32 v55, 16, v16
	v_and_b32_e32 v57, 0xffff0000, v16
	s_waitcnt vmcnt(15)
	v_lshlrev_b32_e32 v62, 16, v18
	v_and_b32_e32 v64, 0xffff0000, v18
	s_waitcnt vmcnt(14)
	v_lshlrev_b32_e32 v63, 16, v20
	v_and_b32_e32 v65, 0xffff0000, v20
	v_lshlrev_b32_e32 v58, 16, v15
	v_lshlrev_b32_e32 v59, 16, v17
	s_waitcnt vmcnt(8)
	v_perm_b32 v40, v122, v120, s98
	v_perm_b32 v41, v126, v124, s98
	v_perm_b32 v100, v122, v120, s99
	v_perm_b32 v101, v126, v124, s99
	v_perm_b32 v106, v123, v121, s98
	v_perm_b32 v107, v127, v125, s98
	v_perm_b32 v112, v123, v121, s99
	v_perm_b32 v113, v127, v125, s99
	v_lshlrev_b32_e32 v69, 16, v41
	v_lshlrev_b32_e32 v68, 16, v40
	v_and_b32_e32 v41, 0xffff0000, v41
	v_and_b32_e32 v40, 0xffff0000, v40
	v_pk_add_f32 v[72:73], v[68:69], v[40:41]
	s_waitcnt vmcnt(7)
; __device__ __forceinline__ f32x4 bf4(v2u u) { return (f32x4){bflo(u.x), bfhi(u.x), bflo(u.y), bfhi(u.y)}; }
; __device__ __forceinline__ v2u pk4(f32x4 v) { v2u o; o.x = pk2(v.x, v.y); o.y = pk2(v.z, v.w); return o; }
; __device__ __forceinline__ void p3_gn_chunk(const Args& a, int ch, int lane) {
;     ...
;     for (int e = 0; e < 4; ++e) { const int t = t0 + e;
;         f32x4 y = bf4(*(const v2u*)(YR + (size_t)t * 1024 + c0));
;         const f32x4 g = bf4(*(const v2u*)(ZB + (size_t)t * 5120 + 4096 + c0)); const float rk = RK[(size_t)t * 16 + head];
;         const float mean = row16_sum((y.x + y.y) + (y.z + y.w)) * (1.f / 64.f);
;         y = y - mean;
;         const float rstd = __builtin_amdgcn_rsqf(row16_sum((y.x * y.x + y.y * y.y) + (y.z * y.z + y.w * y.w)) * (1.f / 64.f) + GN_EPS);
;         const f32x4 v = {vimg[0][e], vimg[1][e], vimg[2][e], vimg[3][e]};
;         f32x4 o = y * rstd * lw + lb + v * rk;
; #pragma unroll
;         for (int k = 0; k < 4; ++k) o[k] *= g[k] * __builtin_amdgcn_rcpf(1.f + __expf(-g[k]));
;         *(v2u*)(Y + (size_t)t * 2048 + c0) = pk4(o); }
	v_lshlrev_b32_e32 v70, 16, v60
	v_add_f32_e32 v33, v72, v73
	v_mul_f32_e32 v14, 0xbfb8aa3b, v70
	v_exp_f32_e32 v14, v14
	v_add_f32_dpp v33, v33, v33 quad_perm:[1,0,3,2] row_mask:0xf bank_mask:0xf bound_ctrl:1
	v_and_b32_e32 v71, 0xffff0000, v60
	v_lshlrev_b32_e32 v60, 16, v61
	v_add_f32_dpp v33, v33, v33 quad_perm:[2,3,0,1] row_mask:0xf bank_mask:0xf bound_ctrl:1
	v_add_f32_e32 v14, 1.0, v14
	v_rcp_f32_e32 v72, v14
	v_add_f32_dpp v33, v33, v33 row_half_mirror row_mask:0xf bank_mask:0xf bound_ctrl:1
	v_and_b32_e32 v61, 0xffff0000, v61
	v_mul_f32_e32 v16, 0xbfb8aa3b, v71
	v_add_f32_dpp v33, v33, v33 row_mirror row_mask:0xf bank_mask:0xf bound_ctrl:1
	v_fmac_f32_e32 v40, 0xbc800000, v33
	v_fmac_f32_e32 v41, 0xbc800000, v33
	v_fmac_f32_e32 v69, 0xbc800000, v33
	v_fmac_f32_e32 v68, 0xbc800000, v33
	v_mov_b32_e32 v76, v69
	v_mov_b32_e32 v77, v41
	v_mov_b32_e32 v69, v40
	v_pk_mul_f32 v[40:41], v[76:77], v[76:77]
	v_pk_mul_f32 v[78:79], v[68:69], v[68:69]
	v_mul_f32_e32 v18, 0xbfb8aa3b, v60
	v_pk_mov_b32 v[80:81], v[78:79], v[40:41] op_sel:[1,0]
	v_mov_b32_e32 v79, v41
	v_pk_add_f32 v[40:41], v[80:81], v[78:79]
	v_mul_f32_e32 v20, 0xbfb8aa3b, v61
	v_add_f32_e32 v14, v40, v41
	v_exp_f32_e32 v16, v16
	v_exp_f32_e32 v18, v18
	v_add_f32_dpp v14, v14, v14 quad_perm:[1,0,3,2] row_mask:0xf bank_mask:0xf bound_ctrl:1
	v_exp_f32_e32 v20, v20
	v_add_f32_e32 v16, 1.0, v16
	v_add_f32_dpp v14, v14, v14 quad_perm:[2,3,0,1] row_mask:0xf bank_mask:0xf bound_ctrl:1
	v_add_f32_e32 v18, 1.0, v18
	v_add_f32_e32 v20, 1.0, v20
	v_add_f32_dpp v14, v14, v14 row_half_mirror row_mask:0xf bank_mask:0xf bound_ctrl:1
	v_rcp_f32_e32 v73, v16
	v_rcp_f32_e32 v74, v18
	v_add_f32_dpp v14, v14, v14 row_mirror row_mask:0xf bank_mask:0xf bound_ctrl:1
	v_fmamk_f32 v14, v14, 0x3c800000, v32
	v_rsq_f32_e32 v14, v14
	v_rcp_f32_e32 v75, v20
	v_pk_mul_f32 v[70:71], v[72:73], v[70:71]
	v_lshlrev_b32_e32 v66, 16, v19
	v_pk_mul_f32 v[40:41], v[76:77], v[14:15] op_sel_hi:[1,0]
	v_pk_mul_f32 v[68:69], v[68:69], v[14:15] op_sel_hi:[1,0]
	v_pk_fma_f32 v[40:41], v[2:3], v[40:41], v[6:7]
	v_pk_fma_f32 v[68:69], v[0:1], v[68:69], v[4:5]
	v_pk_mul_f32 v[60:61], v[74:75], v[60:61]
	s_waitcnt vmcnt(6)
	v_pk_fma_f32 v[40:41], v[10:11], v[62:63], v[40:41] op_sel_hi:[0,1,1]
	v_pk_fma_f32 v[54:55], v[10:11], v[54:55], v[68:69] op_sel_hi:[0,1,1]
	v_pk_mul_f32 v[54:55], v[70:71], v[54:55]
	v_pk_mul_f32 v[40:41], v[60:61], v[40:41]
	v_cvt_pk_bf16_f32 v54, v54, v55
	v_cvt_pk_bf16_f32 v55, v40, v41
	global_store_dwordx2 v[26:27], v[54:55], off
	s_waitcnt vmcnt(1)
	v_mov_b32_e32 v26, v100
	v_mov_b32_e32 v27, v101
	v_mov_b32_e32 v28, v102
	v_mov_b32_e32 v29, v103
	v_mov_b32_e32 v10, v104
	s_nop 0
	v_lshlrev_b32_e32 v67, 16, v21
	s_nop 0
	v_lshlrev_b32_e32 v41, 16, v27
	v_lshlrev_b32_e32 v40, 16, v26
	v_and_b32_e32 v27, 0xffff0000, v27
	v_and_b32_e32 v26, 0xffff0000, v26
	v_pk_add_f32 v[44:45], v[40:41], v[26:27]
	s_nop 0
	v_lshlrev_b32_e32 v42, 16, v28
	v_add_f32_e32 v33, v44, v45
	v_mul_f32_e32 v14, 0xbfb8aa3b, v42
	v_exp_f32_e32 v14, v14
	v_add_f32_dpp v33, v33, v33 quad_perm:[1,0,3,2] row_mask:0xf bank_mask:0xf bound_ctrl:1
	v_and_b32_e32 v43, 0xffff0000, v28
	v_lshlrev_b32_e32 v28, 16, v29
	v_add_f32_dpp v33, v33, v33 quad_perm:[2,3,0,1] row_mask:0xf bank_mask:0xf bound_ctrl:1
	v_add_f32_e32 v14, 1.0, v14
	v_rcp_f32_e32 v44, v14
	v_add_f32_dpp v33, v33, v33 row_half_mirror row_mask:0xf bank_mask:0xf bound_ctrl:1
	v_and_b32_e32 v29, 0xffff0000, v29
	v_mul_f32_e32 v16, 0xbfb8aa3b, v43
	v_add_f32_dpp v33, v33, v33 row_mirror row_mask:0xf bank_mask:0xf bound_ctrl:1
	v_fmac_f32_e32 v26, 0xbc800000, v33
	v_fmac_f32_e32 v27, 0xbc800000, v33
	v_fmac_f32_e32 v41, 0xbc800000, v33
	v_fmac_f32_e32 v40, 0xbc800000, v33
	v_mov_b32_e32 v60, v41
	v_mov_b32_e32 v61, v27
	v_mov_b32_e32 v41, v26
	v_pk_mul_f32 v[26:27], v[60:61], v[60:61]
	v_pk_mul_f32 v[62:63], v[40:41], v[40:41]
	v_mul_f32_e32 v18, 0xbfb8aa3b, v28
	v_pk_mov_b32 v[68:69], v[62:63], v[26:27] op_sel:[1,0]
	v_mov_b32_e32 v63, v27
	v_pk_add_f32 v[26:27], v[68:69], v[62:63]
	v_mul_f32_e32 v20, 0xbfb8aa3b, v29
	v_add_f32_e32 v14, v26, v27
	v_exp_f32_e32 v16, v16
	v_exp_f32_e32 v18, v18
	v_add_f32_dpp v14, v14, v14 quad_perm:[1,0,3,2] row_mask:0xf bank_mask:0xf bound_ctrl:1
	v_exp_f32_e32 v20, v20
	v_add_f32_e32 v16, 1.0, v16
	v_add_f32_dpp v14, v14, v14 quad_perm:[2,3,0,1] row_mask:0xf bank_mask:0xf bound_ctrl:1
	v_add_f32_e32 v18, 1.0, v18
	v_add_f32_e32 v20, 1.0, v20
	v_add_f32_dpp v14, v14, v14 row_half_mirror row_mask:0xf bank_mask:0xf bound_ctrl:1
	v_rcp_f32_e32 v45, v16
	v_rcp_f32_e32 v54, v18
	v_add_f32_dpp v14, v14, v14 row_mirror row_mask:0xf bank_mask:0xf bound_ctrl:1
	v_fmamk_f32 v14, v14, 0x3c800000, v32
	v_rsq_f32_e32 v14, v14
	v_rcp_f32_e32 v55, v20
	v_pk_mul_f32 v[42:43], v[44:45], v[42:43]
	v_pk_mul_f32 v[26:27], v[60:61], v[14:15] op_sel_hi:[1,0]
	v_pk_mul_f32 v[40:41], v[40:41], v[14:15] op_sel_hi:[1,0]
	v_pk_fma_f32 v[26:27], v[2:3], v[26:27], v[6:7]
	v_pk_fma_f32 v[40:41], v[0:1], v[40:41], v[4:5]
	v_pk_mul_f32 v[28:29], v[54:55], v[28:29]
	s_nop 0
	v_pk_fma_f32 v[26:27], v[10:11], v[64:65], v[26:27] op_sel_hi:[0,1,1]
	v_pk_fma_f32 v[40:41], v[10:11], v[56:57], v[40:41] op_sel_hi:[0,1,1]
	v_pk_mul_f32 v[40:41], v[42:43], v[40:41]
	v_pk_mul_f32 v[26:27], v[28:29], v[26:27]
	v_cvt_pk_bf16_f32 v28, v40, v41
	v_cvt_pk_bf16_f32 v29, v26, v27
	global_store_dwordx2 v[34:35], v[28:29], off
	s_nop 0
	v_mov_b32_e32 v26, v106
	v_mov_b32_e32 v27, v107
	v_mov_b32_e32 v28, v108
	v_mov_b32_e32 v29, v109
	v_mov_b32_e32 v10, v110
	s_nop 0
	s_nop 0
	v_lshlrev_b32_e32 v35, 16, v27
	v_lshlrev_b32_e32 v34, 16, v26
	v_and_b32_e32 v27, 0xffff0000, v27
; __device__ __forceinline__ f32x4 bf4(v2u u) { return (f32x4){bflo(u.x), bfhi(u.x), bflo(u.y), bfhi(u.y)}; }
; __device__ __forceinline__ v2u pk4(f32x4 v) { v2u o; o.x = pk2(v.x, v.y); o.y = pk2(v.z, v.w); return o; }
; __device__ __forceinline__ void p3_gn_chunk(const Args& a, int ch, int lane) {
;     ...
;     for (int e = 0; e < 4; ++e) { const int t = t0 + e;
;         f32x4 y = bf4(*(const v2u*)(YR + (size_t)t * 1024 + c0));
;         const f32x4 g = bf4(*(const v2u*)(ZB + (size_t)t * 5120 + 4096 + c0)); const float rk = RK[(size_t)t * 16 + head];
;         const float mean = row16_sum((y.x + y.y) + (y.z + y.w)) * (1.f / 64.f);
;         y = y - mean;
;         const float rstd = __builtin_amdgcn_rsqf(row16_sum((y.x * y.x + y.y * y.y) + (y.z * y.z + y.w * y.w)) * (1.f / 64.f) + GN_EPS);
;         const f32x4 v = {vimg[0][e], vimg[1][e], vimg[2][e], vimg[3][e]};
;         f32x4 o = y * rstd * lw + lb + v * rk;
; #pragma unroll
;         for (int k = 0; k < 4; ++k) o[k] *= g[k] * __builtin_amdgcn_rcpf(1.f + __expf(-g[k]));
;         *(v2u*)(Y + (size_t)t * 2048 + c0) = pk4(o); }
	v_and_b32_e32 v26, 0xffff0000, v26
	v_pk_add_f32 v[42:43], v[34:35], v[26:27]
	s_nop 0
	v_lshlrev_b32_e32 v40, 16, v28
	v_add_f32_e32 v33, v42, v43
	v_mul_f32_e32 v14, 0xbfb8aa3b, v40
	v_exp_f32_e32 v14, v14
	v_add_f32_dpp v33, v33, v33 quad_perm:[1,0,3,2] row_mask:0xf bank_mask:0xf bound_ctrl:1
	v_and_b32_e32 v41, 0xffff0000, v28
	v_lshlrev_b32_e32 v28, 16, v29
	v_add_f32_dpp v33, v33, v33 quad_perm:[2,3,0,1] row_mask:0xf bank_mask:0xf bound_ctrl:1
	v_add_f32_e32 v14, 1.0, v14
	v_rcp_f32_e32 v42, v14
	v_add_f32_dpp v33, v33, v33 row_half_mirror row_mask:0xf bank_mask:0xf bound_ctrl:1
	v_and_b32_e32 v29, 0xffff0000, v29
	v_mul_f32_e32 v16, 0xbfb8aa3b, v41
	v_add_f32_dpp v33, v33, v33 row_mirror row_mask:0xf bank_mask:0xf bound_ctrl:1
	v_fmac_f32_e32 v26, 0xbc800000, v33
	v_fmac_f32_e32 v27, 0xbc800000, v33
	v_fmac_f32_e32 v35, 0xbc800000, v33
	v_fmac_f32_e32 v34, 0xbc800000, v33
	v_mov_b32_e32 v46, v35
	v_mov_b32_e32 v47, v27
	v_mov_b32_e32 v35, v26
	v_pk_mul_f32 v[26:27], v[46:47], v[46:47]
	v_pk_mul_f32 v[50:51], v[34:35], v[34:35]
	v_mul_f32_e32 v18, 0xbfb8aa3b, v28
	v_pk_mov_b32 v[52:53], v[50:51], v[26:27] op_sel:[1,0]
	v_mov_b32_e32 v51, v27
	v_pk_add_f32 v[26:27], v[52:53], v[50:51]
	v_mul_f32_e32 v20, 0xbfb8aa3b, v29
	v_add_f32_e32 v14, v26, v27
	v_exp_f32_e32 v16, v16
	v_exp_f32_e32 v18, v18
	v_add_f32_dpp v14, v14, v14 quad_perm:[1,0,3,2] row_mask:0xf bank_mask:0xf bound_ctrl:1
	v_exp_f32_e32 v20, v20
	v_add_f32_e32 v16, 1.0, v16
	v_add_f32_dpp v14, v14, v14 quad_perm:[2,3,0,1] row_mask:0xf bank_mask:0xf bound_ctrl:1
	v_add_f32_e32 v18, 1.0, v18
	v_add_f32_e32 v20, 1.0, v20
	v_add_f32_dpp v14, v14, v14 row_half_mirror row_mask:0xf bank_mask:0xf bound_ctrl:1
	v_rcp_f32_e32 v43, v16
	v_rcp_f32_e32 v44, v18
	v_add_f32_dpp v14, v14, v14 row_mirror row_mask:0xf bank_mask:0xf bound_ctrl:1
	v_fmamk_f32 v14, v14, 0x3c800000, v32
	v_rsq_f32_e32 v14, v14
	v_rcp_f32_e32 v45, v20
	v_pk_mul_f32 v[40:41], v[42:43], v[40:41]
	v_and_b32_e32 v16, 0xffff0000, v19
	v_pk_mul_f32 v[26:27], v[46:47], v[14:15] op_sel_hi:[1,0]
	v_pk_mul_f32 v[34:35], v[34:35], v[14:15] op_sel_hi:[1,0]
	v_pk_fma_f32 v[26:27], v[2:3], v[26:27], v[6:7]
	v_pk_fma_f32 v[34:35], v[0:1], v[34:35], v[4:5]
	v_pk_mul_f32 v[28:29], v[44:45], v[28:29]
	s_nop 0
	v_pk_fma_f32 v[26:27], v[10:11], v[66:67], v[26:27] op_sel_hi:[0,1,1]
	v_pk_fma_f32 v[34:35], v[10:11], v[58:59], v[34:35] op_sel_hi:[0,1,1]
	v_pk_mul_f32 v[34:35], v[40:41], v[34:35]
	v_pk_mul_f32 v[26:27], v[28:29], v[26:27]
	v_cvt_pk_bf16_f32 v28, v34, v35
	v_cvt_pk_bf16_f32 v29, v26, v27
	global_store_dwordx2 v[36:37], v[28:29], off
	s_nop 0
	v_mov_b32_e32 v26, v112
	v_mov_b32_e32 v27, v113
	v_mov_b32_e32 v28, v114
	v_mov_b32_e32 v29, v115
	v_mov_b32_e32 v10, v116
	s_nop 0
	v_lshlrev_b64 v[34:35], 6, v[22:23]
	v_lshl_add_u64 v[34:35], s[4:5], 0, v[34:35]
	v_lshlrev_b64 v[22:23], 12, v[22:23]
	v_and_b32_e32 v14, 0xffff0000, v15
	v_and_b32_e32 v15, 0xffff0000, v17
	v_and_b32_e32 v17, 0xffff0000, v21
	v_lshl_add_u64 v[22:23], v[24:25], 0, v[22:23]
	s_nop 0
	v_lshlrev_b32_e32 v19, 16, v27
	v_lshlrev_b32_e32 v18, 16, v26
	v_and_b32_e32 v21, 0xffff0000, v27
	v_and_b32_e32 v20, 0xffff0000, v26
	s_nop 0
	v_lshlrev_b32_e32 v24, 16, v28
	v_and_b32_e32 v25, 0xffff0000, v28
	v_lshlrev_b32_e32 v26, 16, v29
	v_and_b32_e32 v27, 0xffff0000, v29
	v_pk_add_f32 v[28:29], v[18:19], v[20:21]
	v_mul_f32_e32 v33, 0xbfb8aa3b, v24
	v_add_f32_e32 v28, v28, v29
	v_mul_f32_e32 v34, 0xbfb8aa3b, v25
	v_mul_f32_e32 v35, 0xbfb8aa3b, v26
	v_add_f32_dpp v28, v28, v28 quad_perm:[1,0,3,2] row_mask:0xf bank_mask:0xf bound_ctrl:1
	v_mul_f32_e32 v36, 0xbfb8aa3b, v27
	v_exp_f32_e32 v29, v33
	v_add_f32_dpp v28, v28, v28 quad_perm:[2,3,0,1] row_mask:0xf bank_mask:0xf bound_ctrl:1
	v_exp_f32_e32 v33, v34
	v_exp_f32_e32 v34, v35
	v_add_f32_dpp v28, v28, v28 row_half_mirror row_mask:0xf bank_mask:0xf bound_ctrl:1
	v_exp_f32_e32 v35, v36
	v_add_f32_e32 v29, 1.0, v29
	v_add_f32_dpp v28, v28, v28 row_mirror row_mask:0xf bank_mask:0xf bound_ctrl:1
	v_fmac_f32_e32 v20, 0xbc800000, v28
	v_fmac_f32_e32 v21, 0xbc800000, v28
	v_fmac_f32_e32 v19, 0xbc800000, v28
	v_fmac_f32_e32 v18, 0xbc800000, v28
	v_mov_b32_e32 v36, v19
	v_mov_b32_e32 v37, v21
	v_mov_b32_e32 v19, v20
	v_pk_mul_f32 v[20:21], v[36:37], v[36:37]
	v_pk_mul_f32 v[38:39], v[18:19], v[18:19]
	v_add_f32_e32 v33, 1.0, v33
	v_pk_mov_b32 v[40:41], v[38:39], v[20:21] op_sel:[1,0]
	v_mov_b32_e32 v39, v21
	v_pk_add_f32 v[20:21], v[40:41], v[38:39]
	v_rcp_f32_e32 v28, v29
	v_add_f32_e32 v20, v20, v21
	v_rcp_f32_e32 v29, v33
	v_add_f32_e32 v34, 1.0, v34
	v_add_f32_dpp v20, v20, v20 quad_perm:[1,0,3,2] row_mask:0xf bank_mask:0xf bound_ctrl:1
	v_add_f32_e32 v35, 1.0, v35
	v_rcp_f32_e32 v34, v34
	v_add_f32_dpp v20, v20, v20 quad_perm:[2,3,0,1] row_mask:0xf bank_mask:0xf bound_ctrl:1
	v_rcp_f32_e32 v35, v35
	v_pk_mul_f32 v[24:25], v[28:29], v[24:25]
	v_add_f32_dpp v20, v20, v20 row_half_mirror row_mask:0xf bank_mask:0xf bound_ctrl:1
	v_pk_mul_f32 v[26:27], v[34:35], v[26:27]
	s_nop 0
	v_add_f32_dpp v20, v20, v20 row_mirror row_mask:0xf bank_mask:0xf bound_ctrl:1
	v_fmamk_f32 v20, v20, 0x3c800000, v32
	v_rsq_f32_e32 v20, v20
	s_nop 0
	v_pk_mul_f32 v[28:29], v[36:37], v[20:21] op_sel_hi:[1,0]
	v_pk_mul_f32 v[18:19], v[18:19], v[20:21] op_sel_hi:[1,0]
	v_pk_fma_f32 v[2:3], v[2:3], v[28:29], v[6:7]
	v_pk_fma_f32 v[0:1], v[0:1], v[18:19], v[4:5]
	s_nop 0
	v_pk_fma_f32 v[2:3], v[10:11], v[16:17], v[2:3] op_sel_hi:[0,1,1]
	v_pk_fma_f32 v[0:1], v[10:11], v[14:15], v[0:1] op_sel_hi:[0,1,1]
	v_pk_mul_f32 v[0:1], v[24:25], v[0:1]
	v_pk_mul_f32 v[2:3], v[26:27], v[2:3]
	v_cvt_pk_bf16_f32 v0, v0, v1
	v_cvt_pk_bf16_f32 v1, v2, v3
	global_store_dwordx2 v[22:23], v[0:1], off
	s_cbranch_scc0 .LBB0_640
